# v73 + deferred W_branch/W_out items moved to the high-ranked waves (max 3 deferred items per wave instead of 4)
# baseline (speedup 1.0000x reference)
;     __device__ __forceinline__ int lane_() const { return lane_id(); }
; __device__ __forceinline__ void phase_prologue(Frame& F) {
;     ...
;         if (r < 6 * I_SQ) { const int m = r / I_SQ; p0_transpose_item(F_w_branch + (size_t)m * D * D, D, D, wbr_t + (size_t)m * D * D, r % I_SQ, F.lane_()); continue; } r -= 6 * I_SQ;
;         if (r < 2 * I_SQ) { const int m = r / I_SQ; p0_transpose_item(F_w_out + (size_t)m * D * D, D, D, wout_t + (size_t)m * D * D, r % I_SQ, F.lane_()); continue; } r -= 2 * I_SQ;
.Ldw_sq:
	s_sub_u32 s58, 0x5ff, s58
	s_cmpk_gt_u32 s58, 0x3ff
	s_cbranch_scc1 .Ldv_done
	v_lshlrev_b32_e32 v185, 16, v183
	v_lshl_add_u32 v185, v184, 4, v185
	s_cmp_lg_u32 s59, 0
	s_cselect_b32 s61, 1, 0
	s_cmpk_gt_u32 s58, 0x2ff
	s_cbranch_scc1 .Ldw_out
	s_mul_i32 s8, s61, 3
	s_lshr_b32 s9, s58, 8
	s_add_u32 s8, s8, s9
	s_mov_b64 s[66:67], s[70:71]
	s_add_u32 s68, s14, 0x3600000
	s_addc_u32 s69, s15, 0
	s_branch .Ldw_go
